# GEMM unit headers: division of the in-group tile index by the (always 4) group size as shift/mask instead of v_rcp + readfirstlane + correction
# baseline (speedup 1.0000x reference)
.LBB0_160:
	s_add_i32 s29, s29, 1
	s_mul_i32 s0, s29, s85
	s_mul_hi_u32 s1, s29, s84
	s_add_i32 s1, s1, s0
	s_mul_i32 s0, s29, s84
	s_add_u32 s40, s0, s2
	s_addc_u32 s41, s1, s3
	v_cmp_gt_i64_e32 vcc, s[40:41], v[144:145]
	v_cmp_lt_i64_e64 s[0:1], s[40:41], v[142:143]
	s_cbranch_vccnz .LBB0_162
	s_ashr_i32 s5, s40, 31
	s_lshr_b32 s5, s5, 29
	s_add_i32 s5, s40, s5
	s_ashr_i32 s7, s5, 3
	s_and_b32 s5, s5, -8
	s_sub_i32 s5, s40, s5
	s_cmp_lt_i32 s5, 0
	s_movk_i32 s36, 0x61
	s_cselect_b32 s36, s36, 0x60
	s_mul_i32 s5, s5, s36
	s_add_i32 s5, s5, s7
	s_mul_hi_i32 s7, s5, 0x2aaaaaab
	s_lshr_b32 s36, s7, 31
	s_ashr_i32 s7, s7, 3
	s_add_i32 s7, s7, s36
	s_lshl_b32 s37, s7, 2
	s_sub_i32 s36, 64, s37
	s_min_i32 s38, s36, 4
	s_mul_i32 s7, s7, 48
	s_sub_i32 s5, s5, s7
	s_lshr_b32 s36, s5, 2
	s_and_b32 s5, s5, 3
	s_add_i32 s38, s37, s5

.LBB0_637:
	s_add_i32 s64, s64, 1
	s_mul_i32 s11, s64, s85
	s_mul_hi_u32 s13, s64, s84
	s_add_i32 s13, s13, s11
	s_mul_i32 s11, s64, s84
	s_add_u32 s16, s11, s2
	s_addc_u32 s17, s13, s3
	v_cmp_gt_i64_e32 vcc, s[16:17], v[144:145]
	v_cmp_lt_i64_e64 s[38:39], s[16:17], v[142:143]
	s_cbranch_vccnz .LBB0_639
	s_ashr_i32 s10, s16, 31
	s_lshr_b32 s10, s10, 29
	s_add_i32 s10, s16, s10
	s_ashr_i32 s11, s10, 3
	s_and_b32 s10, s10, -8
	s_sub_i32 s10, s16, s10
	s_cmp_lt_i32 s10, 0
	s_cselect_b32 s12, s21, 0xa0
	s_mul_i32 s10, s10, s12
	s_add_i32 s10, s10, s11
	s_mul_hi_i32 s11, s10, 0x66666667
	s_lshr_b32 s12, s11, 31
	s_ashr_i32 s11, s11, 5
	s_add_i32 s11, s11, s12
	s_lshl_b32 s12, s11, 2
	s_sub_i32 s13, 64, s12
	s_min_i32 s13, s13, 4
	s_mulk_i32 s11, 0x50
	s_sub_i32 s11, s10, s11
	s_lshr_b32 s10, s11, 2
	s_and_b32 s11, s11, 3
	s_add_i32 s12, s12, s11

.LBB0_675:
	s_ashr_i32 s10, s12, 3
	s_add_i32 s10, s16, s10
	s_ashr_i32 s11, s10, 31
	s_lshr_b32 s11, s11, 24
	s_add_i32 s11, s10, s11
	s_ashr_i32 s12, s11, 8
	s_lshl_b32 s12, s12, 2
	s_sub_i32 s13, 4, s12
	s_min_i32 s13, s13, 4
	s_and_b32 s11, s11, 0xffffff00
	s_sub_i32 s11, s10, s11
	s_lshr_b32 s10, s11, 2
	s_and_b32 s11, s11, 3
	s_add_i32 s12, s12, s11

.LBB0_883:
	s_ashr_i32 s12, s16, 3
	s_add_i32 s12, s18, s12
	s_ashr_i32 s13, s12, 31
	s_lshr_b32 s13, s13, 28
	s_add_i32 s13, s12, s13
	s_ashr_i32 s16, s13, 4
	s_lshl_b32 s16, s16, 2
	s_sub_i32 s17, 64, s16
	s_min_i32 s17, s17, 4
	s_and_b32 s13, s13, -16
	s_sub_i32 s13, s12, s13
	s_lshr_b32 s12, s13, 2
	s_and_b32 s13, s13, 3
	s_add_i32 s16, s16, s13

.LBB0_971:
	s_add_i32 s46, s46, 1
	s_mul_i32 s13, s46, s85
	s_mul_hi_u32 s17, s46, s84
	s_add_i32 s17, s17, s13
	s_mul_i32 s13, s46, s84
	s_add_u32 s18, s13, s2
	s_addc_u32 s19, s17, s3
	v_cmp_gt_i64_e32 vcc, s[18:19], v[144:145]
	v_cmp_lt_i64_e64 s[40:41], s[18:19], v[142:143]
	s_cbranch_vccnz .LBB0_973
	s_ashr_i32 s12, s18, 31
	s_lshr_b32 s12, s12, 29
	s_add_i32 s12, s18, s12
	s_ashr_i32 s13, s12, 3
	s_and_b32 s12, s12, -8
	s_sub_i32 s12, s18, s12
	s_cmp_lt_i32 s12, 0
	s_cselect_b32 s16, s15, 0xb0
	s_mul_i32 s12, s12, s16
	s_add_i32 s12, s12, s13
	s_mul_hi_i32 s13, s12, 0x2e8ba2e9
	s_lshr_b32 s16, s13, 31
	s_ashr_i32 s13, s13, 4
	s_add_i32 s13, s13, s16
	s_lshl_b32 s16, s13, 2
	s_sub_i32 s17, 64, s16
	s_min_i32 s17, s17, 4
	s_mulk_i32 s13, 0x58
	s_sub_i32 s13, s12, s13
	s_lshr_b32 s12, s13, 2
	s_and_b32 s13, s13, 3
	s_add_i32 s16, s16, s13

.LBB0_1049:
	s_ashr_i32 s0, s12, 3
	s_add_i32 s0, s18, s0
	s_ashr_i32 s1, s0, 31
	s_lshr_b32 s1, s1, 28
	s_add_i32 s1, s0, s1
	s_ashr_i32 s12, s1, 4
	s_lshl_b32 s12, s12, 2
	s_sub_i32 s13, 64, s12
	s_min_i32 s13, s13, 4
	s_and_b32 s1, s1, -16
	s_sub_i32 s0, s0, s1
	s_lshr_b32 s33, s0, 2
	s_and_b32 s0, s0, 3
	s_add_i32 s34, s12, s0
